# static prio on waves 0-3 instead of 4-7 (which half is younger check)
# baseline (speedup 1.0000x reference)
; __global__ void __launch_bounds__(NWAVES * 64, 2) fwd_megakernel(Params P) {
;     ...
;     for (int L = vcu; L < 2304; L += G) {
;         int diff, s, head, qb; attn_decode(L, diff, s, head, qb);
;         const float sref = *(const float*)(ws + WS_LAM + 4);
.LBB0_488:
	s_or_b64 exec, exec, s[4:5]
	s_cmpk_gt_i32 s3, 0x8ff
	s_waitcnt lgkmcnt(0)
	s_barrier
	s_cbranch_scc1 .LBB0_634
	v_readlane_b32 s4, v254, 18
	v_readlane_b32 s18, v254, 32
	v_readlane_b32 s5, v254, 19
	v_readlane_b32 s19, v254, 33
	s_add_u32 s4, s18, 0x15100000
	s_addc_u32 s5, s19, 0
	s_add_u32 s52, s18, 0x18100000
	s_addc_u32 s53, s19, 0
	s_add_u32 s61, s18, 0x1b100000
	v_readlane_b32 s10, v254, 24
	s_addc_u32 s66, s19, 0
	v_readlane_b32 s11, v254, 25
	s_add_u32 s10, s18, 0x28000
	v_readlane_b32 s6, v254, 20
	v_readlane_b32 s7, v254, 21
	v_readlane_b32 s8, v254, 22
	v_readlane_b32 s9, v254, 23
	v_readlane_b32 s12, v254, 26
	v_readlane_b32 s13, v254, 27
	v_readlane_b32 s14, v254, 28
	v_readlane_b32 s15, v254, 29
	v_readlane_b32 s16, v254, 30
	v_readlane_b32 s17, v254, 31
	v_writelane_b32 v254, s4, 43
	s_addc_u32 s11, s19, 0
	s_mov_b32 s15, 0
	v_writelane_b32 v254, s5, 44
	s_add_u32 s4, s18, 0x28004
	s_addc_u32 s5, s19, 0
	v_writelane_b32 v254, s4, 45
	v_mov_b32_e32 v0, 0
	s_mov_b32 s62, 0xf800000
	v_writelane_b32 v254, s5, 46
	s_add_u32 s4, s18, 0x4900000
	v_writelane_b32 v254, s4, 47
	s_addc_u32 s4, s19, 0
	v_writelane_b32 v254, s4, 48
	s_add_u32 s4, s18, 0x1e100000
	v_writelane_b32 v254, s4, 49
	s_addc_u32 s4, s19, 0
	v_writelane_b32 v254, s4, 50
	s_add_u32 s4, s18, 0x1b110000
	v_writelane_b32 v254, s4, 51
	s_addc_u32 s4, s19, 0
	v_writelane_b32 v254, s4, 52
	s_add_i32 s4, 0, 0x1ed00
	v_mov_b32_e32 v232, 0x260
	s_movk_i32 s17, 0x4000
	s_movk_i32 s33, 0x100
	s_add_i32 s65, 0, 0x14000
	s_add_i32 s68, 0, 0x1e800
	v_writelane_b32 v254, s4, 53
	v_mov_b32_e32 v233, 0x3c23d70a
	v_mov_b32_e32 v234, 0x358637bd
	s_movk_i32 s70, 0x7fff
	s_mov_b32 s71, 0x41000000
	v_mbcnt_hi_u32_b32 v235, -1, v231
	v_writelane_b32 v254, s1, 54
	v_readfirstlane_b32 s98, v230
	s_lshr_b32 s98, s98, 6
	s_cmp_lt_u32 s98, 4
	s_cbranch_scc0 .Lprio_skip
	s_setprio 1
